# v14 + attention epilogue: xor-1/2/4/8 steps of the per-row sum-of-squares butterfly done with DPP adds instead of ds_bpermute round trips (bit-identical)
# baseline (speedup 1.0000x reference)
.LBB0_539:
	ds_bpermute_b32 v0, v231, v218
	s_lshl_b32 s0, s6, 2
	s_add_i32 s0, s0, 0
	s_ashr_i32 s21, s20, 31
	s_add_i32 s0, s0, 0x1e000
	s_waitcnt lgkmcnt(0)
	v_add_f32_e32 v0, v218, v0
	v_div_scale_f32 v2, s[10:11], v0, v0, 1.0
	v_rcp_f32_e32 v3, v2
	v_div_scale_f32 v4, vcc, 1.0, v0, 1.0
	s_lshl_b64 s[10:11], s[20:21], 12
	v_fma_f32 v5, -v2, v3, 1.0
	v_fmac_f32_e32 v3, v5, v3
	v_mul_f32_e32 v5, v4, v3
	v_fma_f32 v6, -v2, v5, v4
	v_fmac_f32_e32 v5, v6, v3
	v_fma_f32 v2, -v2, v5, v4
	s_add_u32 s7, s16, s10
	v_div_fmas_f32 v2, v2, v3, v5
	s_addc_u32 s9, s17, s11
	s_lshl_b32 s42, s44, 1
	v_div_fixup_f32 v0, v2, v0, 1.0
	v_lshl_add_u32 v2, v215, 2, s0
	s_add_u32 s10, s7, s42
	ds_write_b32 v2, v0
	s_addc_u32 s11, s9, 0
	v_lshlrev_b32_e32 v0, 1, v215
	v_lshl_add_u64 v[2:3], s[10:11], 0, v[0:1]
	v_xor_b32_e32 v0, 1, v233
	v_cmp_lt_i32_e32 vcc, v0, v216
	s_waitcnt lgkmcnt(0)
	v_lshl_add_u32 v6, v214, 4, s0
	s_mov_b32 s9, s87
	v_cndmask_b32_e32 v0, v233, v0, vcc
	v_lshlrev_b32_e32 v250, 2, v0
	v_xor_b32_e32 v0, 2, v233
	v_cmp_lt_i32_e32 vcc, v0, v216
	s_lshl_b64 s[8:9], s[8:9], 3
	s_add_u32 s0, s1, s8
	v_cndmask_b32_e32 v0, v233, v0, vcc
	v_lshlrev_b32_e32 v252, 2, v0
	v_xor_b32_e32 v0, 4, v233
	v_cmp_lt_i32_e32 vcc, v0, v216
	s_addc_u32 s8, s38, s9
	s_ashr_i32 s7, s6, 31
	v_cndmask_b32_e32 v0, v233, v0, vcc
	v_lshlrev_b32_e32 v253, 2, v0
	v_xor_b32_e32 v0, 8, v233
	v_cmp_lt_i32_e32 vcc, v0, v216
	s_lshl_b64 s[6:7], s[6:7], 3
	v_lshlrev_b32_e32 v4, 2, v214
	v_cndmask_b32_e32 v0, v233, v0, vcc
	v_lshlrev_b32_e32 v251, 2, v0
	v_xor_b32_e32 v0, 16, v233
	v_cmp_lt_i32_e32 vcc, v0, v216
	s_add_u32 s6, s0, s6
	s_addc_u32 s7, s8, s7
	v_cndmask_b32_e32 v0, v233, v0, vcc
	v_lshlrev_b32_e32 v249, 2, v0
	ds_read_b32 v0, v6
	v_cmp_eq_u32_e32 vcc, 0, v215
	s_waitcnt lgkmcnt(0)
	v_mul_f32_e32 v7, v48, v0
	v_mul_f32_e32 v5, v64, v0
	v_mul_f32_e32 v8, v7, v7
	v_fmac_f32_e32 v8, v5, v5
	v_mul_f32_e32 v10, v32, v0
	v_fmac_f32_e32 v8, v10, v10
	v_mul_f32_e32 v11, v16, v0
	v_fmac_f32_e32 v8, v11, v11
	s_waitcnt lgkmcnt(0)
	s_nop 1
	v_add_f32_dpp v12, v8, v8 quad_perm:[1,0,3,2] row_mask:0xf bank_mask:0xf
	v_lshlrev_b32_e32 v0, 14, v214
	v_lshl_add_u64 v[8:9], v[2:3], 0, v[0:1]
	v_bfe_u32 v0, v5, 16, 1
	v_add3_u32 v0, v5, v0, s47
	s_waitcnt lgkmcnt(0)
	s_nop 1
	v_add_f32_dpp v12, v12, v12 quad_perm:[2,3,0,1] row_mask:0xf bank_mask:0xf
	global_store_short_d16_hi v[8:9], v0, off
	v_bfe_u32 v0, v7, 16, 1
	v_add3_u32 v0, v7, v0, s47
	global_store_short_d16_hi v[8:9], v0, off offset:64
	s_waitcnt lgkmcnt(0)
	s_nop 1
	v_add_f32_dpp v5, v12, v12 row_half_mirror row_mask:0xf bank_mask:0xf
	v_bfe_u32 v0, v10, 16, 1
	v_add3_u32 v0, v10, v0, s47
	global_store_short_d16_hi v[8:9], v0, off offset:128
	s_waitcnt lgkmcnt(0)
	s_nop 1
	v_add_f32_dpp v0, v5, v5 row_mirror row_mask:0xf bank_mask:0xf
	ds_bpermute_b32 v7, v249, v0
	v_bfe_u32 v5, v11, 16, 1
	v_add3_u32 v5, v11, v5, s47
	global_store_short_d16_hi v[8:9], v5, off offset:192
	v_lshlrev_b32_e32 v5, 3, v4
	s_and_saveexec_b64 s[8:9], vcc
	s_cbranch_execz .LBB0_541
	s_waitcnt lgkmcnt(0)
	v_add_f32_e32 v0, v0, v7
	v_fma_f32 v0, v0, s81, 0.5
	v_trunc_f32_e32 v0, v0
	v_mul_f32_e32 v7, 0x2f800000, v0
	v_floor_f32_e32 v7, v7
	v_fmac_f32_e32 v0, 0xcf800000, v7
	v_cvt_u32_f32_e32 v8, v0
	v_cvt_u32_f32_e32 v9, v7
	global_atomic_add_x2 v5, v[8:9], s[6:7]
.LBB0_541:
	s_or_b64 exec, exec, s[8:9]
	s_waitcnt lgkmcnt(0)
	ds_read_b32 v7, v6 offset:4
	v_mov_b32_e32 v0, 0x1000
	v_lshl_or_b32 v0, v4, 12, v0
	v_lshl_add_u64 v[8:9], v[2:3], 0, v[0:1]
	s_waitcnt lgkmcnt(0)
	v_mul_f32_e32 v0, v65, v7
	v_bfe_u32 v10, v0, 16, 1
	v_add3_u32 v10, v0, v10, s47
	global_store_short_d16_hi v[8:9], v10, off
	v_mul_f32_e32 v10, v49, v7
	v_mul_f32_e32 v11, v10, v10
	v_fmac_f32_e32 v11, v0, v0
	v_bfe_u32 v0, v10, 16, 1
	v_add3_u32 v0, v10, v0, s47
	global_store_short_d16_hi v[8:9], v0, off offset:64
	v_mul_f32_e32 v0, v33, v7
	v_bfe_u32 v10, v0, 16, 1
	v_fmac_f32_e32 v11, v0, v0
	v_add3_u32 v0, v0, v10, s47
	global_store_short_d16_hi v[8:9], v0, off offset:128
	v_mul_f32_e32 v0, v17, v7
	v_bfe_u32 v7, v0, 16, 1
	v_fmac_f32_e32 v11, v0, v0
	v_add3_u32 v0, v0, v7, s47
	global_store_short_d16_hi v[8:9], v0, off offset:192
	s_waitcnt lgkmcnt(0)
	s_nop 1
	v_add_f32_dpp v0, v11, v11 quad_perm:[1,0,3,2] row_mask:0xf bank_mask:0xf
	s_waitcnt lgkmcnt(0)
	s_nop 1
	v_add_f32_dpp v0, v0, v0 quad_perm:[2,3,0,1] row_mask:0xf bank_mask:0xf
	s_waitcnt lgkmcnt(0)
	s_nop 1
	v_add_f32_dpp v0, v0, v0 row_half_mirror row_mask:0xf bank_mask:0xf
	s_waitcnt lgkmcnt(0)
	s_nop 1
	v_add_f32_dpp v0, v0, v0 row_mirror row_mask:0xf bank_mask:0xf
	ds_bpermute_b32 v7, v249, v0
	s_and_saveexec_b64 s[8:9], vcc
	s_cbranch_execz .LBB0_543
	s_waitcnt lgkmcnt(0)
	v_add_f32_e32 v0, v0, v7
	v_fma_f32 v0, v0, s81, 0.5
	v_trunc_f32_e32 v0, v0
	v_mul_f32_e32 v7, 0x2f800000, v0
	v_floor_f32_e32 v7, v7
	v_fmac_f32_e32 v0, 0xcf800000, v7
	v_cvt_u32_f32_e32 v8, v0
	v_cvt_u32_f32_e32 v9, v7
	global_atomic_add_x2 v5, v[8:9], s[6:7] offset:8
.LBB0_543:
	s_or_b64 exec, exec, s[8:9]
	s_waitcnt lgkmcnt(0)
	ds_read_b32 v7, v6 offset:8
	v_mov_b32_e32 v0, 0x2000
	v_lshl_or_b32 v0, v4, 12, v0
	v_lshl_add_u64 v[8:9], v[2:3], 0, v[0:1]
	s_waitcnt lgkmcnt(0)
	v_mul_f32_e32 v0, v66, v7
	v_bfe_u32 v10, v0, 16, 1
	v_add3_u32 v10, v0, v10, s47
	global_store_short_d16_hi v[8:9], v10, off
	v_mul_f32_e32 v10, v50, v7
	v_mul_f32_e32 v11, v10, v10
	v_fmac_f32_e32 v11, v0, v0
	v_bfe_u32 v0, v10, 16, 1
	v_add3_u32 v0, v10, v0, s47
	global_store_short_d16_hi v[8:9], v0, off offset:64
	v_mul_f32_e32 v0, v34, v7
	v_bfe_u32 v10, v0, 16, 1
	v_fmac_f32_e32 v11, v0, v0
	v_add3_u32 v0, v0, v10, s47
	global_store_short_d16_hi v[8:9], v0, off offset:128
	v_mul_f32_e32 v0, v18, v7
	v_bfe_u32 v7, v0, 16, 1
	v_fmac_f32_e32 v11, v0, v0
	v_add3_u32 v0, v0, v7, s47
	global_store_short_d16_hi v[8:9], v0, off offset:192
	s_waitcnt lgkmcnt(0)
	s_nop 1
	v_add_f32_dpp v0, v11, v11 quad_perm:[1,0,3,2] row_mask:0xf bank_mask:0xf
	s_waitcnt lgkmcnt(0)
	s_nop 1
	v_add_f32_dpp v0, v0, v0 quad_perm:[2,3,0,1] row_mask:0xf bank_mask:0xf
	s_waitcnt lgkmcnt(0)
	s_nop 1
	v_add_f32_dpp v0, v0, v0 row_half_mirror row_mask:0xf bank_mask:0xf
	s_waitcnt lgkmcnt(0)
	s_nop 1
	v_add_f32_dpp v0, v0, v0 row_mirror row_mask:0xf bank_mask:0xf
	ds_bpermute_b32 v7, v249, v0
	s_and_saveexec_b64 s[8:9], vcc
	s_cbranch_execz .LBB0_545
	s_waitcnt lgkmcnt(0)
	v_add_f32_e32 v0, v0, v7
	v_fma_f32 v0, v0, s81, 0.5
	v_trunc_f32_e32 v0, v0
	v_mul_f32_e32 v7, 0x2f800000, v0
	v_floor_f32_e32 v7, v7
	v_fmac_f32_e32 v0, 0xcf800000, v7
	v_cvt_u32_f32_e32 v8, v0
	v_cvt_u32_f32_e32 v9, v7
	global_atomic_add_x2 v5, v[8:9], s[6:7] offset:16
.LBB0_545:
	s_or_b64 exec, exec, s[8:9]
	s_waitcnt lgkmcnt(0)
	ds_read_b32 v7, v6 offset:12
	v_mov_b32_e32 v0, 0x3000
	v_lshl_or_b32 v0, v4, 12, v0
	v_lshl_add_u64 v[8:9], v[2:3], 0, v[0:1]
	s_waitcnt lgkmcnt(0)
	v_mul_f32_e32 v0, v67, v7
	v_bfe_u32 v10, v0, 16, 1
	v_add3_u32 v10, v0, v10, s47
	global_store_short_d16_hi v[8:9], v10, off
	v_mul_f32_e32 v10, v51, v7
	v_mul_f32_e32 v11, v10, v10
	v_fmac_f32_e32 v11, v0, v0
	v_bfe_u32 v0, v10, 16, 1
	v_add3_u32 v0, v10, v0, s47
	global_store_short_d16_hi v[8:9], v0, off offset:64
	v_mul_f32_e32 v0, v35, v7
	v_bfe_u32 v10, v0, 16, 1
	v_fmac_f32_e32 v11, v0, v0
	v_add3_u32 v0, v0, v10, s47
	global_store_short_d16_hi v[8:9], v0, off offset:128
	v_mul_f32_e32 v0, v19, v7
	v_bfe_u32 v7, v0, 16, 1
	v_fmac_f32_e32 v11, v0, v0
	v_add3_u32 v0, v0, v7, s47
	global_store_short_d16_hi v[8:9], v0, off offset:192
	s_waitcnt lgkmcnt(0)
	s_nop 1
	v_add_f32_dpp v0, v11, v11 quad_perm:[1,0,3,2] row_mask:0xf bank_mask:0xf
	s_waitcnt lgkmcnt(0)
	s_nop 1
	v_add_f32_dpp v0, v0, v0 quad_perm:[2,3,0,1] row_mask:0xf bank_mask:0xf
	s_waitcnt lgkmcnt(0)
	s_nop 1
	v_add_f32_dpp v0, v0, v0 row_half_mirror row_mask:0xf bank_mask:0xf
	s_waitcnt lgkmcnt(0)
	s_nop 1
	v_add_f32_dpp v0, v0, v0 row_mirror row_mask:0xf bank_mask:0xf
	ds_bpermute_b32 v7, v249, v0
	s_and_saveexec_b64 s[8:9], vcc
	s_cbranch_execz .LBB0_547
	s_waitcnt lgkmcnt(0)
	v_add_f32_e32 v0, v0, v7
	v_fma_f32 v0, v0, s81, 0.5
	v_trunc_f32_e32 v0, v0
	v_mul_f32_e32 v7, 0x2f800000, v0
	v_floor_f32_e32 v7, v7
	v_fmac_f32_e32 v0, 0xcf800000, v7
	v_cvt_u32_f32_e32 v8, v0
	v_cvt_u32_f32_e32 v9, v7
	global_atomic_add_x2 v5, v[8:9], s[6:7] offset:24
.LBB0_547:
	s_or_b64 exec, exec, s[8:9]
	s_waitcnt lgkmcnt(0)
	ds_read_b32 v7, v6 offset:32
	v_mov_b32_e32 v0, 0x8000
	v_lshl_or_b32 v0, v4, 12, v0
	v_lshl_add_u64 v[8:9], v[2:3], 0, v[0:1]
	s_waitcnt lgkmcnt(0)
	v_mul_f32_e32 v0, v68, v7
	v_bfe_u32 v10, v0, 16, 1
	v_add3_u32 v10, v0, v10, s47
	global_store_short_d16_hi v[8:9], v10, off
	v_mul_f32_e32 v10, v52, v7
	v_mul_f32_e32 v11, v10, v10
	v_fmac_f32_e32 v11, v0, v0
	v_bfe_u32 v0, v10, 16, 1
	v_add3_u32 v0, v10, v0, s47
	global_store_short_d16_hi v[8:9], v0, off offset:64
	v_mul_f32_e32 v0, v36, v7
	v_bfe_u32 v10, v0, 16, 1
	v_fmac_f32_e32 v11, v0, v0
	v_add3_u32 v0, v0, v10, s47
	global_store_short_d16_hi v[8:9], v0, off offset:128
	v_mul_f32_e32 v0, v20, v7
	v_bfe_u32 v7, v0, 16, 1
	v_fmac_f32_e32 v11, v0, v0
	v_add3_u32 v0, v0, v7, s47
	global_store_short_d16_hi v[8:9], v0, off offset:192
	s_waitcnt lgkmcnt(0)
	s_nop 1
	v_add_f32_dpp v0, v11, v11 quad_perm:[1,0,3,2] row_mask:0xf bank_mask:0xf
	s_waitcnt lgkmcnt(0)
	s_nop 1
	v_add_f32_dpp v0, v0, v0 quad_perm:[2,3,0,1] row_mask:0xf bank_mask:0xf
	s_waitcnt lgkmcnt(0)
	s_nop 1
	v_add_f32_dpp v0, v0, v0 row_half_mirror row_mask:0xf bank_mask:0xf
	s_waitcnt lgkmcnt(0)
	s_nop 1
	v_add_f32_dpp v0, v0, v0 row_mirror row_mask:0xf bank_mask:0xf
	ds_bpermute_b32 v7, v249, v0
	s_and_saveexec_b64 s[8:9], vcc
	s_cbranch_execz .LBB0_549
	s_waitcnt lgkmcnt(0)
	v_add_f32_e32 v0, v0, v7
	v_fma_f32 v0, v0, s81, 0.5
	v_trunc_f32_e32 v0, v0
	v_mul_f32_e32 v7, 0x2f800000, v0
	v_floor_f32_e32 v7, v7
	v_fmac_f32_e32 v0, 0xcf800000, v7
	v_cvt_u32_f32_e32 v8, v0
	v_cvt_u32_f32_e32 v9, v7
	global_atomic_add_x2 v5, v[8:9], s[6:7] offset:64
.LBB0_549:
	s_or_b64 exec, exec, s[8:9]
	s_waitcnt lgkmcnt(0)
	ds_read_b32 v7, v6 offset:36
	v_mov_b32_e32 v0, 0x9000
	v_lshl_or_b32 v0, v4, 12, v0
	v_lshl_add_u64 v[8:9], v[2:3], 0, v[0:1]
	s_waitcnt lgkmcnt(0)
	v_mul_f32_e32 v0, v69, v7
	v_bfe_u32 v10, v0, 16, 1
	v_add3_u32 v10, v0, v10, s47
	global_store_short_d16_hi v[8:9], v10, off
	v_mul_f32_e32 v10, v53, v7
	v_mul_f32_e32 v11, v10, v10
	v_fmac_f32_e32 v11, v0, v0
	v_bfe_u32 v0, v10, 16, 1
	v_add3_u32 v0, v10, v0, s47
	global_store_short_d16_hi v[8:9], v0, off offset:64
	v_mul_f32_e32 v0, v37, v7
	v_bfe_u32 v10, v0, 16, 1
	v_fmac_f32_e32 v11, v0, v0
	v_add3_u32 v0, v0, v10, s47
	global_store_short_d16_hi v[8:9], v0, off offset:128
	v_mul_f32_e32 v0, v21, v7
	v_bfe_u32 v7, v0, 16, 1
	v_fmac_f32_e32 v11, v0, v0
	v_add3_u32 v0, v0, v7, s47
	global_store_short_d16_hi v[8:9], v0, off offset:192
	s_waitcnt lgkmcnt(0)
	s_nop 1
	v_add_f32_dpp v0, v11, v11 quad_perm:[1,0,3,2] row_mask:0xf bank_mask:0xf
	s_waitcnt lgkmcnt(0)
	s_nop 1
	v_add_f32_dpp v0, v0, v0 quad_perm:[2,3,0,1] row_mask:0xf bank_mask:0xf
	s_waitcnt lgkmcnt(0)
	s_nop 1
	v_add_f32_dpp v0, v0, v0 row_half_mirror row_mask:0xf bank_mask:0xf
	s_waitcnt lgkmcnt(0)
	s_nop 1
	v_add_f32_dpp v0, v0, v0 row_mirror row_mask:0xf bank_mask:0xf
	ds_bpermute_b32 v7, v249, v0
	s_and_saveexec_b64 s[8:9], vcc
	s_cbranch_execz .LBB0_551
	s_waitcnt lgkmcnt(0)
	v_add_f32_e32 v0, v0, v7
	v_fma_f32 v0, v0, s81, 0.5
	v_trunc_f32_e32 v0, v0
	v_mul_f32_e32 v7, 0x2f800000, v0
	v_floor_f32_e32 v7, v7
	v_fmac_f32_e32 v0, 0xcf800000, v7
	v_cvt_u32_f32_e32 v8, v0
	v_cvt_u32_f32_e32 v9, v7
	global_atomic_add_x2 v5, v[8:9], s[6:7] offset:72
.LBB0_551:
	s_or_b64 exec, exec, s[8:9]
	s_waitcnt lgkmcnt(0)
	ds_read_b32 v7, v6 offset:40
	v_mov_b32_e32 v0, 0xa000
	v_lshl_or_b32 v0, v4, 12, v0
	v_lshl_add_u64 v[8:9], v[2:3], 0, v[0:1]
	s_waitcnt lgkmcnt(0)
	v_mul_f32_e32 v0, v70, v7
	v_bfe_u32 v10, v0, 16, 1
	v_add3_u32 v10, v0, v10, s47
	global_store_short_d16_hi v[8:9], v10, off
	v_mul_f32_e32 v10, v54, v7
	v_mul_f32_e32 v11, v10, v10
	v_fmac_f32_e32 v11, v0, v0
	v_bfe_u32 v0, v10, 16, 1
	v_add3_u32 v0, v10, v0, s47
	global_store_short_d16_hi v[8:9], v0, off offset:64
	v_mul_f32_e32 v0, v38, v7
	v_bfe_u32 v10, v0, 16, 1
	v_fmac_f32_e32 v11, v0, v0
	v_add3_u32 v0, v0, v10, s47
	global_store_short_d16_hi v[8:9], v0, off offset:128
	v_mul_f32_e32 v0, v22, v7
	v_bfe_u32 v7, v0, 16, 1
	v_fmac_f32_e32 v11, v0, v0
	v_add3_u32 v0, v0, v7, s47
	global_store_short_d16_hi v[8:9], v0, off offset:192
	s_waitcnt lgkmcnt(0)
	s_nop 1
	v_add_f32_dpp v0, v11, v11 quad_perm:[1,0,3,2] row_mask:0xf bank_mask:0xf
	s_waitcnt lgkmcnt(0)
	s_nop 1
	v_add_f32_dpp v0, v0, v0 quad_perm:[2,3,0,1] row_mask:0xf bank_mask:0xf
	s_waitcnt lgkmcnt(0)
	s_nop 1
	v_add_f32_dpp v0, v0, v0 row_half_mirror row_mask:0xf bank_mask:0xf
	s_waitcnt lgkmcnt(0)
	s_nop 1
	v_add_f32_dpp v0, v0, v0 row_mirror row_mask:0xf bank_mask:0xf
	ds_bpermute_b32 v7, v249, v0
	s_and_saveexec_b64 s[8:9], vcc
	s_cbranch_execz .LBB0_553
	s_waitcnt lgkmcnt(0)
	v_add_f32_e32 v0, v0, v7
	v_fma_f32 v0, v0, s81, 0.5
	v_trunc_f32_e32 v0, v0
	v_mul_f32_e32 v7, 0x2f800000, v0
	v_floor_f32_e32 v7, v7
	v_fmac_f32_e32 v0, 0xcf800000, v7
	v_cvt_u32_f32_e32 v8, v0
	v_cvt_u32_f32_e32 v9, v7
	global_atomic_add_x2 v5, v[8:9], s[6:7] offset:80
.LBB0_553:
	s_or_b64 exec, exec, s[8:9]
	s_waitcnt lgkmcnt(0)
	ds_read_b32 v7, v6 offset:44
	v_mov_b32_e32 v0, 0xb000
	v_lshl_or_b32 v0, v4, 12, v0
	v_lshl_add_u64 v[8:9], v[2:3], 0, v[0:1]
	s_waitcnt lgkmcnt(0)
	v_mul_f32_e32 v0, v71, v7
	v_bfe_u32 v10, v0, 16, 1
	v_add3_u32 v10, v0, v10, s47
	global_store_short_d16_hi v[8:9], v10, off
	v_mul_f32_e32 v10, v55, v7
	v_mul_f32_e32 v11, v10, v10
	v_fmac_f32_e32 v11, v0, v0
	v_bfe_u32 v0, v10, 16, 1
	v_add3_u32 v0, v10, v0, s47
	global_store_short_d16_hi v[8:9], v0, off offset:64
	v_mul_f32_e32 v0, v39, v7
	v_bfe_u32 v10, v0, 16, 1
	v_fmac_f32_e32 v11, v0, v0
	v_add3_u32 v0, v0, v10, s47
	global_store_short_d16_hi v[8:9], v0, off offset:128
	v_mul_f32_e32 v0, v23, v7
	v_bfe_u32 v7, v0, 16, 1
	v_fmac_f32_e32 v11, v0, v0
	v_add3_u32 v0, v0, v7, s47
	global_store_short_d16_hi v[8:9], v0, off offset:192
	s_waitcnt lgkmcnt(0)
	s_nop 1
	v_add_f32_dpp v0, v11, v11 quad_perm:[1,0,3,2] row_mask:0xf bank_mask:0xf
	s_waitcnt lgkmcnt(0)
	s_nop 1
	v_add_f32_dpp v0, v0, v0 quad_perm:[2,3,0,1] row_mask:0xf bank_mask:0xf
	s_waitcnt lgkmcnt(0)
	s_nop 1
	v_add_f32_dpp v0, v0, v0 row_half_mirror row_mask:0xf bank_mask:0xf
	s_waitcnt lgkmcnt(0)
	s_nop 1
	v_add_f32_dpp v0, v0, v0 row_mirror row_mask:0xf bank_mask:0xf
	ds_bpermute_b32 v7, v249, v0
	s_and_saveexec_b64 s[8:9], vcc
	s_cbranch_execz .LBB0_555
	s_waitcnt lgkmcnt(0)
	v_add_f32_e32 v0, v0, v7
	v_fma_f32 v0, v0, s81, 0.5
	v_trunc_f32_e32 v0, v0
	v_mul_f32_e32 v7, 0x2f800000, v0
	v_floor_f32_e32 v7, v7
	v_fmac_f32_e32 v0, 0xcf800000, v7
	v_cvt_u32_f32_e32 v8, v0
	v_cvt_u32_f32_e32 v9, v7
	global_atomic_add_x2 v5, v[8:9], s[6:7] offset:88
.LBB0_555:
	s_or_b64 exec, exec, s[8:9]
	s_waitcnt lgkmcnt(0)
	ds_read_b32 v7, v6 offset:64
	v_mov_b32_e32 v0, 0x10000
	v_lshl_or_b32 v0, v4, 12, v0
	v_lshl_add_u64 v[8:9], v[2:3], 0, v[0:1]
	s_waitcnt lgkmcnt(0)
	v_mul_f32_e32 v0, v72, v7
	v_bfe_u32 v10, v0, 16, 1
	v_add3_u32 v10, v0, v10, s47
	global_store_short_d16_hi v[8:9], v10, off
	v_mul_f32_e32 v10, v56, v7
	v_mul_f32_e32 v11, v10, v10
	v_fmac_f32_e32 v11, v0, v0
	v_bfe_u32 v0, v10, 16, 1
	v_add3_u32 v0, v10, v0, s47
	global_store_short_d16_hi v[8:9], v0, off offset:64
	v_mul_f32_e32 v0, v40, v7
	v_bfe_u32 v10, v0, 16, 1
	v_fmac_f32_e32 v11, v0, v0
	v_add3_u32 v0, v0, v10, s47
	global_store_short_d16_hi v[8:9], v0, off offset:128
	v_mul_f32_e32 v0, v24, v7
	v_bfe_u32 v7, v0, 16, 1
	v_fmac_f32_e32 v11, v0, v0
	v_add3_u32 v0, v0, v7, s47
	global_store_short_d16_hi v[8:9], v0, off offset:192
	s_waitcnt lgkmcnt(0)
	s_nop 1
	v_add_f32_dpp v0, v11, v11 quad_perm:[1,0,3,2] row_mask:0xf bank_mask:0xf
	s_waitcnt lgkmcnt(0)
	s_nop 1
	v_add_f32_dpp v0, v0, v0 quad_perm:[2,3,0,1] row_mask:0xf bank_mask:0xf
	s_waitcnt lgkmcnt(0)
	s_nop 1
	v_add_f32_dpp v0, v0, v0 row_half_mirror row_mask:0xf bank_mask:0xf
	s_waitcnt lgkmcnt(0)
	s_nop 1
	v_add_f32_dpp v0, v0, v0 row_mirror row_mask:0xf bank_mask:0xf
	ds_bpermute_b32 v7, v249, v0
	s_and_saveexec_b64 s[8:9], vcc
	s_cbranch_execz .LBB0_557
	s_waitcnt lgkmcnt(0)
	v_add_f32_e32 v0, v0, v7
	v_fma_f32 v0, v0, s81, 0.5
	v_trunc_f32_e32 v0, v0
	v_mul_f32_e32 v7, 0x2f800000, v0
	v_floor_f32_e32 v7, v7
	v_fmac_f32_e32 v0, 0xcf800000, v7
	v_cvt_u32_f32_e32 v8, v0
	v_cvt_u32_f32_e32 v9, v7
	global_atomic_add_x2 v5, v[8:9], s[6:7] offset:128
.LBB0_557:
	s_or_b64 exec, exec, s[8:9]
	s_waitcnt lgkmcnt(0)
	ds_read_b32 v7, v6 offset:68
	v_mov_b32_e32 v0, 0x11000
	v_lshl_or_b32 v0, v4, 12, v0
	v_lshl_add_u64 v[8:9], v[2:3], 0, v[0:1]
	s_waitcnt lgkmcnt(0)
	v_mul_f32_e32 v0, v73, v7
	v_bfe_u32 v10, v0, 16, 1
	v_add3_u32 v10, v0, v10, s47
	global_store_short_d16_hi v[8:9], v10, off
	v_mul_f32_e32 v10, v57, v7
	v_mul_f32_e32 v11, v10, v10
	v_fmac_f32_e32 v11, v0, v0
	v_bfe_u32 v0, v10, 16, 1
	v_add3_u32 v0, v10, v0, s47
	global_store_short_d16_hi v[8:9], v0, off offset:64
	v_mul_f32_e32 v0, v41, v7
	v_bfe_u32 v10, v0, 16, 1
	v_fmac_f32_e32 v11, v0, v0
	v_add3_u32 v0, v0, v10, s47
	global_store_short_d16_hi v[8:9], v0, off offset:128
	v_mul_f32_e32 v0, v25, v7
	v_bfe_u32 v7, v0, 16, 1
	v_fmac_f32_e32 v11, v0, v0
	v_add3_u32 v0, v0, v7, s47
	global_store_short_d16_hi v[8:9], v0, off offset:192
	s_waitcnt lgkmcnt(0)
	s_nop 1
	v_add_f32_dpp v0, v11, v11 quad_perm:[1,0,3,2] row_mask:0xf bank_mask:0xf
	s_waitcnt lgkmcnt(0)
	s_nop 1
	v_add_f32_dpp v0, v0, v0 quad_perm:[2,3,0,1] row_mask:0xf bank_mask:0xf
	s_waitcnt lgkmcnt(0)
	s_nop 1
	v_add_f32_dpp v0, v0, v0 row_half_mirror row_mask:0xf bank_mask:0xf
	s_waitcnt lgkmcnt(0)
	s_nop 1
	v_add_f32_dpp v0, v0, v0 row_mirror row_mask:0xf bank_mask:0xf
	ds_bpermute_b32 v7, v249, v0
	s_and_saveexec_b64 s[8:9], vcc
	s_cbranch_execz .LBB0_559
	s_waitcnt lgkmcnt(0)
	v_add_f32_e32 v0, v0, v7
	v_fma_f32 v0, v0, s81, 0.5
	v_trunc_f32_e32 v0, v0
	v_mul_f32_e32 v7, 0x2f800000, v0
	v_floor_f32_e32 v7, v7
	v_fmac_f32_e32 v0, 0xcf800000, v7
	v_cvt_u32_f32_e32 v8, v0
	v_cvt_u32_f32_e32 v9, v7
	global_atomic_add_x2 v5, v[8:9], s[6:7] offset:136
.LBB0_559:
	s_or_b64 exec, exec, s[8:9]
	s_waitcnt lgkmcnt(0)
	ds_read_b32 v7, v6 offset:72
	v_mov_b32_e32 v0, 0x12000
	v_lshl_or_b32 v0, v4, 12, v0
	v_lshl_add_u64 v[8:9], v[2:3], 0, v[0:1]
	s_waitcnt lgkmcnt(0)
	v_mul_f32_e32 v0, v74, v7
	v_bfe_u32 v10, v0, 16, 1
	v_add3_u32 v10, v0, v10, s47
	global_store_short_d16_hi v[8:9], v10, off
	v_mul_f32_e32 v10, v58, v7
	v_mul_f32_e32 v11, v10, v10
	v_fmac_f32_e32 v11, v0, v0
	v_bfe_u32 v0, v10, 16, 1
	v_add3_u32 v0, v10, v0, s47
	global_store_short_d16_hi v[8:9], v0, off offset:64
	v_mul_f32_e32 v0, v42, v7
	v_bfe_u32 v10, v0, 16, 1
	v_fmac_f32_e32 v11, v0, v0
	v_add3_u32 v0, v0, v10, s47
	global_store_short_d16_hi v[8:9], v0, off offset:128
	v_mul_f32_e32 v0, v26, v7
	v_bfe_u32 v7, v0, 16, 1
	v_fmac_f32_e32 v11, v0, v0
	v_add3_u32 v0, v0, v7, s47
	global_store_short_d16_hi v[8:9], v0, off offset:192
	s_waitcnt lgkmcnt(0)
	s_nop 1
	v_add_f32_dpp v0, v11, v11 quad_perm:[1,0,3,2] row_mask:0xf bank_mask:0xf
	s_waitcnt lgkmcnt(0)
	s_nop 1
	v_add_f32_dpp v0, v0, v0 quad_perm:[2,3,0,1] row_mask:0xf bank_mask:0xf
	s_waitcnt lgkmcnt(0)
	s_nop 1
	v_add_f32_dpp v0, v0, v0 row_half_mirror row_mask:0xf bank_mask:0xf
	s_waitcnt lgkmcnt(0)
	s_nop 1
	v_add_f32_dpp v0, v0, v0 row_mirror row_mask:0xf bank_mask:0xf
	ds_bpermute_b32 v7, v249, v0
	s_and_saveexec_b64 s[8:9], vcc
	s_cbranch_execz .LBB0_561
	s_waitcnt lgkmcnt(0)
	v_add_f32_e32 v0, v0, v7
	v_fma_f32 v0, v0, s81, 0.5
	v_trunc_f32_e32 v0, v0
	v_mul_f32_e32 v7, 0x2f800000, v0
	v_floor_f32_e32 v7, v7
	v_fmac_f32_e32 v0, 0xcf800000, v7
	v_cvt_u32_f32_e32 v8, v0
	v_cvt_u32_f32_e32 v9, v7
	global_atomic_add_x2 v5, v[8:9], s[6:7] offset:144
.LBB0_561:
	s_or_b64 exec, exec, s[8:9]
	s_waitcnt lgkmcnt(0)
	ds_read_b32 v7, v6 offset:76
	v_mov_b32_e32 v0, 0x13000
	v_lshl_or_b32 v0, v4, 12, v0
	v_lshl_add_u64 v[8:9], v[2:3], 0, v[0:1]
	s_waitcnt lgkmcnt(0)
	v_mul_f32_e32 v0, v75, v7
	v_bfe_u32 v10, v0, 16, 1
	v_add3_u32 v10, v0, v10, s47
	global_store_short_d16_hi v[8:9], v10, off
	v_mul_f32_e32 v10, v59, v7
	v_mul_f32_e32 v11, v10, v10
	v_fmac_f32_e32 v11, v0, v0
	v_bfe_u32 v0, v10, 16, 1
	v_add3_u32 v0, v10, v0, s47
	global_store_short_d16_hi v[8:9], v0, off offset:64
	v_mul_f32_e32 v0, v43, v7
	v_bfe_u32 v10, v0, 16, 1
	v_fmac_f32_e32 v11, v0, v0
	v_add3_u32 v0, v0, v10, s47
	global_store_short_d16_hi v[8:9], v0, off offset:128
	v_mul_f32_e32 v0, v27, v7
	v_bfe_u32 v7, v0, 16, 1
	v_fmac_f32_e32 v11, v0, v0
	v_add3_u32 v0, v0, v7, s47
	global_store_short_d16_hi v[8:9], v0, off offset:192
	s_waitcnt lgkmcnt(0)
	s_nop 1
	v_add_f32_dpp v0, v11, v11 quad_perm:[1,0,3,2] row_mask:0xf bank_mask:0xf
	s_waitcnt lgkmcnt(0)
	s_nop 1
	v_add_f32_dpp v0, v0, v0 quad_perm:[2,3,0,1] row_mask:0xf bank_mask:0xf
	s_waitcnt lgkmcnt(0)
	s_nop 1
	v_add_f32_dpp v0, v0, v0 row_half_mirror row_mask:0xf bank_mask:0xf
	s_waitcnt lgkmcnt(0)
	s_nop 1
	v_add_f32_dpp v0, v0, v0 row_mirror row_mask:0xf bank_mask:0xf
	ds_bpermute_b32 v7, v249, v0
	s_and_saveexec_b64 s[8:9], vcc
	s_cbranch_execz .LBB0_563
	s_waitcnt lgkmcnt(0)
	v_add_f32_e32 v0, v0, v7
	v_fma_f32 v0, v0, s81, 0.5
	v_trunc_f32_e32 v0, v0
	v_mul_f32_e32 v7, 0x2f800000, v0
	v_floor_f32_e32 v7, v7
	v_fmac_f32_e32 v0, 0xcf800000, v7
	v_cvt_u32_f32_e32 v8, v0
	v_cvt_u32_f32_e32 v9, v7
	global_atomic_add_x2 v5, v[8:9], s[6:7] offset:152
.LBB0_563:
	s_or_b64 exec, exec, s[8:9]
	s_waitcnt lgkmcnt(0)
	ds_read_b32 v7, v6 offset:96
	v_mov_b32_e32 v0, 0x18000
	v_lshl_or_b32 v0, v4, 12, v0
	v_lshl_add_u64 v[8:9], v[2:3], 0, v[0:1]
	s_waitcnt lgkmcnt(0)
	v_mul_f32_e32 v0, v76, v7
	v_bfe_u32 v10, v0, 16, 1
	v_add3_u32 v10, v0, v10, s47
	global_store_short_d16_hi v[8:9], v10, off
	v_mul_f32_e32 v10, v60, v7
	v_mul_f32_e32 v11, v10, v10
	v_fmac_f32_e32 v11, v0, v0
	v_bfe_u32 v0, v10, 16, 1
	v_add3_u32 v0, v10, v0, s47
	global_store_short_d16_hi v[8:9], v0, off offset:64
	v_mul_f32_e32 v0, v44, v7
	v_bfe_u32 v10, v0, 16, 1
	v_fmac_f32_e32 v11, v0, v0
	v_add3_u32 v0, v0, v10, s47
	global_store_short_d16_hi v[8:9], v0, off offset:128
	v_mul_f32_e32 v0, v28, v7
	v_bfe_u32 v7, v0, 16, 1
	v_fmac_f32_e32 v11, v0, v0
	v_add3_u32 v0, v0, v7, s47
	global_store_short_d16_hi v[8:9], v0, off offset:192
	s_waitcnt lgkmcnt(0)
	s_nop 1
	v_add_f32_dpp v0, v11, v11 quad_perm:[1,0,3,2] row_mask:0xf bank_mask:0xf
	s_waitcnt lgkmcnt(0)
	s_nop 1
	v_add_f32_dpp v0, v0, v0 quad_perm:[2,3,0,1] row_mask:0xf bank_mask:0xf
	s_waitcnt lgkmcnt(0)
	s_nop 1
	v_add_f32_dpp v0, v0, v0 row_half_mirror row_mask:0xf bank_mask:0xf
	s_waitcnt lgkmcnt(0)
	s_nop 1
	v_add_f32_dpp v0, v0, v0 row_mirror row_mask:0xf bank_mask:0xf
	ds_bpermute_b32 v7, v249, v0
	s_and_saveexec_b64 s[8:9], vcc
	s_cbranch_execz .LBB0_565
	s_waitcnt lgkmcnt(0)
	v_add_f32_e32 v0, v0, v7
	v_fma_f32 v0, v0, s81, 0.5
	v_trunc_f32_e32 v0, v0
	v_mul_f32_e32 v7, 0x2f800000, v0
	v_floor_f32_e32 v7, v7
	v_fmac_f32_e32 v0, 0xcf800000, v7
	v_cvt_u32_f32_e32 v8, v0
	v_cvt_u32_f32_e32 v9, v7
	global_atomic_add_x2 v5, v[8:9], s[6:7] offset:192
.LBB0_565:
	s_or_b64 exec, exec, s[8:9]
	s_waitcnt lgkmcnt(0)
	ds_read_b32 v7, v6 offset:100
	v_mov_b32_e32 v0, 0x19000
	v_lshl_or_b32 v0, v4, 12, v0
	v_lshl_add_u64 v[8:9], v[2:3], 0, v[0:1]
	s_waitcnt lgkmcnt(0)
	v_mul_f32_e32 v0, v77, v7
	v_bfe_u32 v10, v0, 16, 1
	v_add3_u32 v10, v0, v10, s47
	global_store_short_d16_hi v[8:9], v10, off
	v_mul_f32_e32 v10, v61, v7
	v_mul_f32_e32 v11, v10, v10
	v_fmac_f32_e32 v11, v0, v0
	v_bfe_u32 v0, v10, 16, 1
	v_add3_u32 v0, v10, v0, s47
	global_store_short_d16_hi v[8:9], v0, off offset:64
	v_mul_f32_e32 v0, v45, v7
	v_bfe_u32 v10, v0, 16, 1
	v_fmac_f32_e32 v11, v0, v0
	v_add3_u32 v0, v0, v10, s47
	global_store_short_d16_hi v[8:9], v0, off offset:128
	v_mul_f32_e32 v0, v29, v7
	v_bfe_u32 v7, v0, 16, 1
	v_fmac_f32_e32 v11, v0, v0
	v_add3_u32 v0, v0, v7, s47
	global_store_short_d16_hi v[8:9], v0, off offset:192
	s_waitcnt lgkmcnt(0)
	s_nop 1
	v_add_f32_dpp v0, v11, v11 quad_perm:[1,0,3,2] row_mask:0xf bank_mask:0xf
	s_waitcnt lgkmcnt(0)
	s_nop 1
	v_add_f32_dpp v0, v0, v0 quad_perm:[2,3,0,1] row_mask:0xf bank_mask:0xf
	s_waitcnt lgkmcnt(0)
	s_nop 1
	v_add_f32_dpp v0, v0, v0 row_half_mirror row_mask:0xf bank_mask:0xf
	s_waitcnt lgkmcnt(0)
	s_nop 1
	v_add_f32_dpp v0, v0, v0 row_mirror row_mask:0xf bank_mask:0xf
	ds_bpermute_b32 v7, v249, v0
	s_and_saveexec_b64 s[8:9], vcc
	s_cbranch_execz .LBB0_567
	s_waitcnt lgkmcnt(0)
	v_add_f32_e32 v0, v0, v7
	v_fma_f32 v0, v0, s81, 0.5
	v_trunc_f32_e32 v0, v0
	v_mul_f32_e32 v7, 0x2f800000, v0
	v_floor_f32_e32 v7, v7
	v_fmac_f32_e32 v0, 0xcf800000, v7
	v_cvt_u32_f32_e32 v8, v0
	v_cvt_u32_f32_e32 v9, v7
	global_atomic_add_x2 v5, v[8:9], s[6:7] offset:200
.LBB0_567:
	s_or_b64 exec, exec, s[8:9]
	s_waitcnt lgkmcnt(0)
	ds_read_b32 v7, v6 offset:104
	v_mov_b32_e32 v0, 0x1a000
	v_lshl_or_b32 v0, v4, 12, v0
	v_lshl_add_u64 v[8:9], v[2:3], 0, v[0:1]
	s_waitcnt lgkmcnt(0)
	v_mul_f32_e32 v0, v78, v7
	v_bfe_u32 v10, v0, 16, 1
	v_add3_u32 v10, v0, v10, s47
	global_store_short_d16_hi v[8:9], v10, off
	v_mul_f32_e32 v10, v62, v7
	v_mul_f32_e32 v11, v10, v10
	v_fmac_f32_e32 v11, v0, v0
	v_bfe_u32 v0, v10, 16, 1
	v_add3_u32 v0, v10, v0, s47
	global_store_short_d16_hi v[8:9], v0, off offset:64
	v_mul_f32_e32 v0, v46, v7
	v_bfe_u32 v10, v0, 16, 1
	v_fmac_f32_e32 v11, v0, v0
	v_add3_u32 v0, v0, v10, s47
	global_store_short_d16_hi v[8:9], v0, off offset:128
	v_mul_f32_e32 v0, v30, v7
	v_bfe_u32 v7, v0, 16, 1
	v_fmac_f32_e32 v11, v0, v0
	v_add3_u32 v0, v0, v7, s47
	global_store_short_d16_hi v[8:9], v0, off offset:192
	s_waitcnt lgkmcnt(0)
	s_nop 1
	v_add_f32_dpp v0, v11, v11 quad_perm:[1,0,3,2] row_mask:0xf bank_mask:0xf
	s_waitcnt lgkmcnt(0)
	s_nop 1
	v_add_f32_dpp v0, v0, v0 quad_perm:[2,3,0,1] row_mask:0xf bank_mask:0xf
	s_waitcnt lgkmcnt(0)
	s_nop 1
	v_add_f32_dpp v0, v0, v0 row_half_mirror row_mask:0xf bank_mask:0xf
	s_waitcnt lgkmcnt(0)
	s_nop 1
	v_add_f32_dpp v0, v0, v0 row_mirror row_mask:0xf bank_mask:0xf
	ds_bpermute_b32 v7, v249, v0
	s_and_saveexec_b64 s[8:9], vcc
	s_cbranch_execz .LBB0_569
	s_waitcnt lgkmcnt(0)
	v_add_f32_e32 v0, v0, v7
	v_fma_f32 v0, v0, s81, 0.5
	v_trunc_f32_e32 v0, v0
	v_mul_f32_e32 v7, 0x2f800000, v0
	v_floor_f32_e32 v7, v7
	v_fmac_f32_e32 v0, 0xcf800000, v7
	v_cvt_u32_f32_e32 v8, v0
	v_cvt_u32_f32_e32 v9, v7
	global_atomic_add_x2 v5, v[8:9], s[6:7] offset:208
.LBB0_569:
	s_or_b64 exec, exec, s[8:9]
	ds_read_b32 v0, v6 offset:108
	s_waitcnt lgkmcnt(0)
	v_mul_f32_e32 v9, v63, v0
	v_mul_f32_e32 v8, v79, v0
	v_mul_f32_e32 v6, v9, v9
	v_mul_f32_e32 v10, v47, v0
	v_fmac_f32_e32 v6, v8, v8
	v_fmac_f32_e32 v6, v10, v10
	v_mul_f32_e32 v11, v31, v0
	v_fmac_f32_e32 v6, v11, v11
	s_waitcnt lgkmcnt(0)
	s_nop 1
	v_add_f32_dpp v12, v6, v6 quad_perm:[1,0,3,2] row_mask:0xf bank_mask:0xf
	v_mov_b32_e32 v0, 0x1b000
	v_lshl_or_b32 v0, v4, 12, v0
	v_lshl_add_u64 v[6:7], v[2:3], 0, v[0:1]
	v_bfe_u32 v3, v8, 16, 1
	s_waitcnt lgkmcnt(0)
	s_nop 1
	v_add_f32_dpp v0, v12, v12 quad_perm:[2,3,0,1] row_mask:0xf bank_mask:0xf
	v_add3_u32 v3, v8, v3, s47
	global_store_short_d16_hi v[6:7], v3, off
	v_bfe_u32 v3, v9, 16, 1
	v_add3_u32 v3, v9, v3, s47
	s_waitcnt lgkmcnt(0)
	s_nop 1
	v_add_f32_dpp v0, v0, v0 row_half_mirror row_mask:0xf bank_mask:0xf
	global_store_short_d16_hi v[6:7], v3, off offset:64
	v_bfe_u32 v3, v10, 16, 1
	v_add3_u32 v3, v10, v3, s47
	global_store_short_d16_hi v[6:7], v3, off offset:128
	s_waitcnt lgkmcnt(0)
	s_nop 1
	v_add_f32_dpp v0, v0, v0 row_mirror row_mask:0xf bank_mask:0xf
	ds_bpermute_b32 v2, v249, v0
	v_bfe_u32 v3, v11, 16, 1
	v_add3_u32 v3, v11, v3, s47
	global_store_short_d16_hi v[6:7], v3, off offset:192
	s_and_saveexec_b64 s[8:9], vcc
	s_cbranch_execz .LBB0_571
	s_waitcnt lgkmcnt(0)
	v_add_f32_e32 v0, v0, v2
	v_fma_f32 v0, v0, s81, 0.5
	v_trunc_f32_e32 v0, v0
	v_mul_f32_e32 v2, 0x2f800000, v0
	v_floor_f32_e32 v3, v2
	v_fmac_f32_e32 v0, 0xcf800000, v3
	v_cvt_u32_f32_e32 v2, v0
	v_cvt_u32_f32_e32 v3, v3
	global_atomic_add_x2 v5, v[2:3], s[6:7] offset:216

.LBB0_583:
	ds_bpermute_b32 v66, v231, v0
	s_lshl_b32 s0, s6, 2
	s_add_i32 s0, s0, 0
	s_ashr_i32 s21, s20, 31
	s_add_i32 s0, s0, 0x1e000
	s_waitcnt lgkmcnt(0)
	v_add_f32_e32 v0, v0, v66
	v_div_scale_f32 v66, s[10:11], v0, v0, 1.0
	v_rcp_f32_e32 v67, v66
	v_div_scale_f32 v68, vcc, 1.0, v0, 1.0
	s_lshl_b64 s[10:11], s[20:21], 12
	v_fma_f32 v69, -v66, v67, 1.0
	v_fmac_f32_e32 v67, v69, v67
	v_mul_f32_e32 v69, v68, v67
	v_fma_f32 v70, -v66, v69, v68
	v_fmac_f32_e32 v69, v70, v67
	v_fma_f32 v66, -v66, v69, v68
	v_div_fmas_f32 v66, v66, v67, v69
	s_add_u32 s7, s16, s10
	v_div_fixup_f32 v0, v66, v0, 1.0
	v_lshl_add_u32 v66, v238, 2, s0
	s_addc_u32 s9, s17, s11
	ds_write_b32 v66, v0
	s_add_u32 s10, s7, s42
	s_waitcnt lgkmcnt(0)
	s_addc_u32 s11, s9, 0
	v_lshlrev_b32_e32 v0, 1, v238
	v_lshl_add_u32 v69, v237, 4, s0
	v_lshl_add_u64 v[66:67], s[10:11], 0, v[0:1]
	ds_read_b32 v0, v69
	s_ashr_i32 s9, s8, 31
	s_lshl_b64 s[8:9], s[8:9], 3
	s_add_u32 s0, s1, s8
	s_addc_u32 s8, s38, s9
	s_waitcnt lgkmcnt(0)
	v_mul_f32_e32 v34, v34, v0
	v_mul_f32_e32 v50, v50, v0
	v_mul_f32_e32 v70, v34, v34
	v_fmac_f32_e32 v70, v50, v50
	v_mul_f32_e32 v18, v18, v0
	v_fmac_f32_e32 v70, v18, v18
	v_mul_f32_e32 v2, v2, v0
	v_fmac_f32_e32 v70, v2, v2
	s_ashr_i32 s7, s6, 31
	s_lshl_b64 s[6:7], s[6:7], 3
	v_lshlrev_b32_e32 v68, 2, v237
	s_add_u32 s6, s0, s6
	s_waitcnt lgkmcnt(0)
	s_nop 1
	v_add_f32_dpp v72, v70, v70 quad_perm:[1,0,3,2] row_mask:0xf bank_mask:0xf
	v_lshlrev_b32_e32 v0, 14, v237
	v_lshl_add_u64 v[70:71], v[66:67], 0, v[0:1]
	v_bfe_u32 v0, v50, 16, 1
	v_add3_u32 v0, v50, v0, s47
	s_waitcnt lgkmcnt(0)
	s_nop 1
	v_add_f32_dpp v72, v72, v72 quad_perm:[2,3,0,1] row_mask:0xf bank_mask:0xf
	global_store_short_d16_hi v[70:71], v0, off
	v_bfe_u32 v0, v34, 16, 1
	v_add3_u32 v0, v34, v0, s47
	global_store_short_d16_hi v[70:71], v0, off offset:64
	s_waitcnt lgkmcnt(0)
	s_nop 1
	v_add_f32_dpp v34, v72, v72 row_half_mirror row_mask:0xf bank_mask:0xf
	v_bfe_u32 v0, v18, 16, 1
	v_add3_u32 v0, v18, v0, s47
	global_store_short_d16_hi v[70:71], v0, off offset:128
	v_cmp_eq_u32_e32 vcc, 0, v238
	s_waitcnt lgkmcnt(0)
	s_nop 1
	v_add_f32_dpp v0, v34, v34 row_mirror row_mask:0xf bank_mask:0xf
	ds_bpermute_b32 v18, v249, v0
	v_bfe_u32 v34, v2, 16, 1
	v_add3_u32 v2, v2, v34, s47
	s_addc_u32 s7, s8, s7
	global_store_short_d16_hi v[70:71], v2, off offset:192
	v_lshlrev_b32_e32 v2, 3, v68
	s_and_saveexec_b64 s[8:9], vcc
	s_cbranch_execz .LBB0_585
	s_waitcnt lgkmcnt(0)
	v_add_f32_e32 v0, v0, v18
	v_fma_f32 v0, v0, s81, 0.5
	v_trunc_f32_e32 v0, v0
	v_mul_f32_e32 v18, 0x2f800000, v0
	v_floor_f32_e32 v18, v18
	v_fmac_f32_e32 v0, 0xcf800000, v18
	v_cvt_u32_f32_e32 v70, v0
	v_cvt_u32_f32_e32 v71, v18
	global_atomic_add_x2 v2, v[70:71], s[6:7]
.LBB0_585:
	s_or_b64 exec, exec, s[8:9]
	s_waitcnt lgkmcnt(0)
	ds_read_b32 v18, v69 offset:4
	v_mov_b32_e32 v0, 0x1000
	v_lshl_or_b32 v0, v68, 12, v0
	v_lshl_add_u64 v[70:71], v[66:67], 0, v[0:1]
	s_waitcnt lgkmcnt(0)
	v_mul_f32_e32 v0, v51, v18
	v_bfe_u32 v34, v0, 16, 1
	v_add3_u32 v34, v0, v34, s47
	global_store_short_d16_hi v[70:71], v34, off
	v_mul_f32_e32 v34, v35, v18
	v_mul_f32_e32 v35, v34, v34
	v_fmac_f32_e32 v35, v0, v0
	v_bfe_u32 v0, v34, 16, 1
	v_add3_u32 v0, v34, v0, s47
	global_store_short_d16_hi v[70:71], v0, off offset:64
	v_mul_f32_e32 v0, v19, v18
	v_bfe_u32 v19, v0, 16, 1
	v_fmac_f32_e32 v35, v0, v0
	v_add3_u32 v0, v0, v19, s47
	global_store_short_d16_hi v[70:71], v0, off offset:128
	v_mul_f32_e32 v0, v3, v18
	v_bfe_u32 v3, v0, 16, 1
	v_fmac_f32_e32 v35, v0, v0
	v_add3_u32 v0, v0, v3, s47
	global_store_short_d16_hi v[70:71], v0, off offset:192
	s_waitcnt lgkmcnt(0)
	s_nop 1
	v_add_f32_dpp v0, v35, v35 quad_perm:[1,0,3,2] row_mask:0xf bank_mask:0xf
	s_waitcnt lgkmcnt(0)
	s_nop 1
	v_add_f32_dpp v0, v0, v0 quad_perm:[2,3,0,1] row_mask:0xf bank_mask:0xf
	s_waitcnt lgkmcnt(0)
	s_nop 1
	v_add_f32_dpp v0, v0, v0 row_half_mirror row_mask:0xf bank_mask:0xf
	s_waitcnt lgkmcnt(0)
	s_nop 1
	v_add_f32_dpp v0, v0, v0 row_mirror row_mask:0xf bank_mask:0xf
	ds_bpermute_b32 v3, v249, v0
	s_and_saveexec_b64 s[8:9], vcc
	s_cbranch_execz .LBB0_587
	s_waitcnt lgkmcnt(0)
	v_add_f32_e32 v0, v0, v3
	v_fma_f32 v0, v0, s81, 0.5
	v_trunc_f32_e32 v0, v0
	v_mul_f32_e32 v3, 0x2f800000, v0
	v_floor_f32_e32 v3, v3
	v_fmac_f32_e32 v0, 0xcf800000, v3
	v_cvt_u32_f32_e32 v18, v0
	v_cvt_u32_f32_e32 v19, v3
	global_atomic_add_x2 v2, v[18:19], s[6:7] offset:8
.LBB0_587:
	s_or_b64 exec, exec, s[8:9]
	s_waitcnt lgkmcnt(0)
	ds_read_b32 v3, v69 offset:8
	v_mov_b32_e32 v0, 0x2000
	v_lshl_or_b32 v0, v68, 12, v0
	v_lshl_add_u64 v[18:19], v[66:67], 0, v[0:1]
	s_waitcnt lgkmcnt(0)
	v_mul_f32_e32 v0, v52, v3
	v_bfe_u32 v34, v0, 16, 1
	v_add3_u32 v34, v0, v34, s47
	global_store_short_d16_hi v[18:19], v34, off
	v_mul_f32_e32 v34, v36, v3
	v_mul_f32_e32 v35, v34, v34
	v_fmac_f32_e32 v35, v0, v0
	v_bfe_u32 v0, v34, 16, 1
	v_add3_u32 v0, v34, v0, s47
	global_store_short_d16_hi v[18:19], v0, off offset:64
	v_mul_f32_e32 v0, v20, v3
	v_bfe_u32 v20, v0, 16, 1
	v_fmac_f32_e32 v35, v0, v0
	v_add3_u32 v0, v0, v20, s47
	global_store_short_d16_hi v[18:19], v0, off offset:128
	v_mul_f32_e32 v0, v4, v3
	v_bfe_u32 v3, v0, 16, 1
	v_fmac_f32_e32 v35, v0, v0
	v_add3_u32 v0, v0, v3, s47
	global_store_short_d16_hi v[18:19], v0, off offset:192
	s_waitcnt lgkmcnt(0)
	s_nop 1
	v_add_f32_dpp v0, v35, v35 quad_perm:[1,0,3,2] row_mask:0xf bank_mask:0xf
	s_waitcnt lgkmcnt(0)
	s_nop 1
	v_add_f32_dpp v0, v0, v0 quad_perm:[2,3,0,1] row_mask:0xf bank_mask:0xf
	s_waitcnt lgkmcnt(0)
	s_nop 1
	v_add_f32_dpp v0, v0, v0 row_half_mirror row_mask:0xf bank_mask:0xf
	s_waitcnt lgkmcnt(0)
	s_nop 1
	v_add_f32_dpp v0, v0, v0 row_mirror row_mask:0xf bank_mask:0xf
	ds_bpermute_b32 v3, v249, v0
	s_and_saveexec_b64 s[8:9], vcc
	s_cbranch_execz .LBB0_589
	s_waitcnt lgkmcnt(0)
	v_add_f32_e32 v0, v0, v3
	v_fma_f32 v0, v0, s81, 0.5
	v_trunc_f32_e32 v0, v0
	v_mul_f32_e32 v3, 0x2f800000, v0
	v_floor_f32_e32 v3, v3
	v_fmac_f32_e32 v0, 0xcf800000, v3
	v_cvt_u32_f32_e32 v18, v0
	v_cvt_u32_f32_e32 v19, v3
	global_atomic_add_x2 v2, v[18:19], s[6:7] offset:16
.LBB0_589:
	s_or_b64 exec, exec, s[8:9]
	s_waitcnt lgkmcnt(0)
	ds_read_b32 v3, v69 offset:12
	v_mov_b32_e32 v0, 0x3000
	v_lshl_or_b32 v0, v68, 12, v0
	v_lshl_add_u64 v[18:19], v[66:67], 0, v[0:1]
	s_waitcnt lgkmcnt(0)
	v_mul_f32_e32 v0, v53, v3
	v_bfe_u32 v4, v0, 16, 1
	v_add3_u32 v4, v0, v4, s47
	global_store_short_d16_hi v[18:19], v4, off
	v_mul_f32_e32 v4, v37, v3
	v_mul_f32_e32 v20, v4, v4
	v_fmac_f32_e32 v20, v0, v0
	v_bfe_u32 v0, v4, 16, 1
	v_add3_u32 v0, v4, v0, s47
	global_store_short_d16_hi v[18:19], v0, off offset:64
	v_mul_f32_e32 v0, v21, v3
	v_bfe_u32 v4, v0, 16, 1
	v_fmac_f32_e32 v20, v0, v0
	v_add3_u32 v0, v0, v4, s47
	global_store_short_d16_hi v[18:19], v0, off offset:128
	v_mul_f32_e32 v0, v5, v3
	v_bfe_u32 v3, v0, 16, 1
	v_fmac_f32_e32 v20, v0, v0
	v_add3_u32 v0, v0, v3, s47
	global_store_short_d16_hi v[18:19], v0, off offset:192
	s_waitcnt lgkmcnt(0)
	s_nop 1
	v_add_f32_dpp v0, v20, v20 quad_perm:[1,0,3,2] row_mask:0xf bank_mask:0xf
	s_waitcnt lgkmcnt(0)
	s_nop 1
	v_add_f32_dpp v0, v0, v0 quad_perm:[2,3,0,1] row_mask:0xf bank_mask:0xf
	s_waitcnt lgkmcnt(0)
	s_nop 1
	v_add_f32_dpp v0, v0, v0 row_half_mirror row_mask:0xf bank_mask:0xf
	s_waitcnt lgkmcnt(0)
	s_nop 1
	v_add_f32_dpp v0, v0, v0 row_mirror row_mask:0xf bank_mask:0xf
	ds_bpermute_b32 v3, v249, v0
	s_and_saveexec_b64 s[8:9], vcc
	s_cbranch_execz .LBB0_591
	s_waitcnt lgkmcnt(0)
	v_add_f32_e32 v0, v0, v3
	v_fma_f32 v0, v0, s81, 0.5
	v_trunc_f32_e32 v0, v0
	v_mul_f32_e32 v3, 0x2f800000, v0
	v_floor_f32_e32 v3, v3
	v_fmac_f32_e32 v0, 0xcf800000, v3
	v_cvt_u32_f32_e32 v4, v0
	v_cvt_u32_f32_e32 v5, v3
	global_atomic_add_x2 v2, v[4:5], s[6:7] offset:24
.LBB0_591:
	s_or_b64 exec, exec, s[8:9]
	s_waitcnt lgkmcnt(0)
	ds_read_b32 v3, v69 offset:32
	v_mov_b32_e32 v0, 0x8000
	v_lshl_or_b32 v0, v68, 12, v0
	v_lshl_add_u64 v[4:5], v[66:67], 0, v[0:1]
	s_waitcnt lgkmcnt(0)
	v_mul_f32_e32 v0, v54, v3
	v_bfe_u32 v18, v0, 16, 1
	v_add3_u32 v18, v0, v18, s47
	global_store_short_d16_hi v[4:5], v18, off
	v_mul_f32_e32 v18, v38, v3
	v_mul_f32_e32 v19, v18, v18
	v_fmac_f32_e32 v19, v0, v0
	v_bfe_u32 v0, v18, 16, 1
	v_add3_u32 v0, v18, v0, s47
	global_store_short_d16_hi v[4:5], v0, off offset:64
	v_mul_f32_e32 v0, v22, v3
	v_bfe_u32 v18, v0, 16, 1
	v_fmac_f32_e32 v19, v0, v0
	v_add3_u32 v0, v0, v18, s47
	global_store_short_d16_hi v[4:5], v0, off offset:128
	v_mul_f32_e32 v0, v6, v3
	v_bfe_u32 v3, v0, 16, 1
	v_fmac_f32_e32 v19, v0, v0
	v_add3_u32 v0, v0, v3, s47
	global_store_short_d16_hi v[4:5], v0, off offset:192
	s_waitcnt lgkmcnt(0)
	s_nop 1
	v_add_f32_dpp v0, v19, v19 quad_perm:[1,0,3,2] row_mask:0xf bank_mask:0xf
	s_waitcnt lgkmcnt(0)
	s_nop 1
	v_add_f32_dpp v0, v0, v0 quad_perm:[2,3,0,1] row_mask:0xf bank_mask:0xf
	s_waitcnt lgkmcnt(0)
	s_nop 1
	v_add_f32_dpp v0, v0, v0 row_half_mirror row_mask:0xf bank_mask:0xf
	s_waitcnt lgkmcnt(0)
	s_nop 1
	v_add_f32_dpp v0, v0, v0 row_mirror row_mask:0xf bank_mask:0xf
	ds_bpermute_b32 v3, v249, v0
	s_and_saveexec_b64 s[8:9], vcc
	s_cbranch_execz .LBB0_593
	s_waitcnt lgkmcnt(0)
	v_add_f32_e32 v0, v0, v3
	v_fma_f32 v0, v0, s81, 0.5
	v_trunc_f32_e32 v0, v0
	v_mul_f32_e32 v3, 0x2f800000, v0
	v_floor_f32_e32 v3, v3
	v_fmac_f32_e32 v0, 0xcf800000, v3
	v_cvt_u32_f32_e32 v4, v0
	v_cvt_u32_f32_e32 v5, v3
	global_atomic_add_x2 v2, v[4:5], s[6:7] offset:64
.LBB0_593:
	s_or_b64 exec, exec, s[8:9]
	s_waitcnt lgkmcnt(0)
	ds_read_b32 v3, v69 offset:36
	v_mov_b32_e32 v0, 0x9000
	v_lshl_or_b32 v0, v68, 12, v0
	v_lshl_add_u64 v[4:5], v[66:67], 0, v[0:1]
	s_waitcnt lgkmcnt(0)
	v_mul_f32_e32 v0, v55, v3
	v_bfe_u32 v6, v0, 16, 1
	v_add3_u32 v6, v0, v6, s47
	global_store_short_d16_hi v[4:5], v6, off
	v_mul_f32_e32 v6, v39, v3
	v_mul_f32_e32 v18, v6, v6
	v_fmac_f32_e32 v18, v0, v0
	v_bfe_u32 v0, v6, 16, 1
	v_add3_u32 v0, v6, v0, s47
	global_store_short_d16_hi v[4:5], v0, off offset:64
	v_mul_f32_e32 v0, v23, v3
	v_bfe_u32 v6, v0, 16, 1
	v_fmac_f32_e32 v18, v0, v0
	v_add3_u32 v0, v0, v6, s47
	global_store_short_d16_hi v[4:5], v0, off offset:128
	v_mul_f32_e32 v0, v7, v3
	v_bfe_u32 v3, v0, 16, 1
	v_fmac_f32_e32 v18, v0, v0
	v_add3_u32 v0, v0, v3, s47
	global_store_short_d16_hi v[4:5], v0, off offset:192
	s_waitcnt lgkmcnt(0)
	s_nop 1
	v_add_f32_dpp v0, v18, v18 quad_perm:[1,0,3,2] row_mask:0xf bank_mask:0xf
	s_waitcnt lgkmcnt(0)
	s_nop 1
	v_add_f32_dpp v0, v0, v0 quad_perm:[2,3,0,1] row_mask:0xf bank_mask:0xf
	s_waitcnt lgkmcnt(0)
	s_nop 1
	v_add_f32_dpp v0, v0, v0 row_half_mirror row_mask:0xf bank_mask:0xf
	s_waitcnt lgkmcnt(0)
	s_nop 1
	v_add_f32_dpp v0, v0, v0 row_mirror row_mask:0xf bank_mask:0xf
	ds_bpermute_b32 v3, v249, v0
	s_and_saveexec_b64 s[8:9], vcc
	s_cbranch_execz .LBB0_595
	s_waitcnt lgkmcnt(0)
	v_add_f32_e32 v0, v0, v3
	v_fma_f32 v0, v0, s81, 0.5
	v_trunc_f32_e32 v0, v0
	v_mul_f32_e32 v3, 0x2f800000, v0
	v_floor_f32_e32 v3, v3
	v_fmac_f32_e32 v0, 0xcf800000, v3
	v_cvt_u32_f32_e32 v4, v0
	v_cvt_u32_f32_e32 v5, v3
	global_atomic_add_x2 v2, v[4:5], s[6:7] offset:72
.LBB0_595:
	s_or_b64 exec, exec, s[8:9]
	s_waitcnt lgkmcnt(0)
	ds_read_b32 v3, v69 offset:40
	v_mov_b32_e32 v0, 0xa000
	v_lshl_or_b32 v0, v68, 12, v0
	v_lshl_add_u64 v[4:5], v[66:67], 0, v[0:1]
	s_waitcnt lgkmcnt(0)
	v_mul_f32_e32 v0, v56, v3
	v_bfe_u32 v6, v0, 16, 1
	v_add3_u32 v6, v0, v6, s47
	global_store_short_d16_hi v[4:5], v6, off
	v_mul_f32_e32 v6, v40, v3
	v_mul_f32_e32 v7, v6, v6
	v_fmac_f32_e32 v7, v0, v0
	v_bfe_u32 v0, v6, 16, 1
	v_add3_u32 v0, v6, v0, s47
	global_store_short_d16_hi v[4:5], v0, off offset:64
	v_mul_f32_e32 v0, v24, v3
	v_bfe_u32 v6, v0, 16, 1
	v_fmac_f32_e32 v7, v0, v0
	v_add3_u32 v0, v0, v6, s47
	global_store_short_d16_hi v[4:5], v0, off offset:128
	v_mul_f32_e32 v0, v8, v3
	v_bfe_u32 v3, v0, 16, 1
	v_fmac_f32_e32 v7, v0, v0
	v_add3_u32 v0, v0, v3, s47
	global_store_short_d16_hi v[4:5], v0, off offset:192
	s_waitcnt lgkmcnt(0)
	s_nop 1
	v_add_f32_dpp v0, v7, v7 quad_perm:[1,0,3,2] row_mask:0xf bank_mask:0xf
	s_waitcnt lgkmcnt(0)
	s_nop 1
	v_add_f32_dpp v0, v0, v0 quad_perm:[2,3,0,1] row_mask:0xf bank_mask:0xf
	s_waitcnt lgkmcnt(0)
	s_nop 1
	v_add_f32_dpp v0, v0, v0 row_half_mirror row_mask:0xf bank_mask:0xf
	s_waitcnt lgkmcnt(0)
	s_nop 1
	v_add_f32_dpp v0, v0, v0 row_mirror row_mask:0xf bank_mask:0xf
	ds_bpermute_b32 v3, v249, v0
	s_and_saveexec_b64 s[8:9], vcc
	s_cbranch_execz .LBB0_597
	s_waitcnt lgkmcnt(0)
	v_add_f32_e32 v0, v0, v3
	v_fma_f32 v0, v0, s81, 0.5
	v_trunc_f32_e32 v0, v0
	v_mul_f32_e32 v3, 0x2f800000, v0
	v_floor_f32_e32 v3, v3
	v_fmac_f32_e32 v0, 0xcf800000, v3
	v_cvt_u32_f32_e32 v4, v0
	v_cvt_u32_f32_e32 v5, v3
	global_atomic_add_x2 v2, v[4:5], s[6:7] offset:80
.LBB0_597:
	s_or_b64 exec, exec, s[8:9]
	s_waitcnt lgkmcnt(0)
	ds_read_b32 v3, v69 offset:44
	v_mov_b32_e32 v0, 0xb000
	v_lshl_or_b32 v0, v68, 12, v0
	v_lshl_add_u64 v[4:5], v[66:67], 0, v[0:1]
	s_waitcnt lgkmcnt(0)
	v_mul_f32_e32 v0, v57, v3
	v_bfe_u32 v6, v0, 16, 1
	v_add3_u32 v6, v0, v6, s47
	global_store_short_d16_hi v[4:5], v6, off
	v_mul_f32_e32 v6, v41, v3
	v_mul_f32_e32 v7, v6, v6
	v_fmac_f32_e32 v7, v0, v0
	v_bfe_u32 v0, v6, 16, 1
	v_add3_u32 v0, v6, v0, s47
	global_store_short_d16_hi v[4:5], v0, off offset:64
	v_mul_f32_e32 v0, v25, v3
	v_bfe_u32 v6, v0, 16, 1
	v_fmac_f32_e32 v7, v0, v0
	v_add3_u32 v0, v0, v6, s47
	global_store_short_d16_hi v[4:5], v0, off offset:128
	v_mul_f32_e32 v0, v9, v3
	v_bfe_u32 v3, v0, 16, 1
	v_fmac_f32_e32 v7, v0, v0
	v_add3_u32 v0, v0, v3, s47
	global_store_short_d16_hi v[4:5], v0, off offset:192
	s_waitcnt lgkmcnt(0)
	s_nop 1
	v_add_f32_dpp v0, v7, v7 quad_perm:[1,0,3,2] row_mask:0xf bank_mask:0xf
	s_waitcnt lgkmcnt(0)
	s_nop 1
	v_add_f32_dpp v0, v0, v0 quad_perm:[2,3,0,1] row_mask:0xf bank_mask:0xf
	s_waitcnt lgkmcnt(0)
	s_nop 1
	v_add_f32_dpp v0, v0, v0 row_half_mirror row_mask:0xf bank_mask:0xf
	s_waitcnt lgkmcnt(0)
	s_nop 1
	v_add_f32_dpp v0, v0, v0 row_mirror row_mask:0xf bank_mask:0xf
	ds_bpermute_b32 v3, v249, v0
	s_and_saveexec_b64 s[8:9], vcc
	s_cbranch_execz .LBB0_599
	s_waitcnt lgkmcnt(0)
	v_add_f32_e32 v0, v0, v3
	v_fma_f32 v0, v0, s81, 0.5
	v_trunc_f32_e32 v0, v0
	v_mul_f32_e32 v3, 0x2f800000, v0
	v_floor_f32_e32 v3, v3
	v_fmac_f32_e32 v0, 0xcf800000, v3
	v_cvt_u32_f32_e32 v4, v0
	v_cvt_u32_f32_e32 v5, v3
	global_atomic_add_x2 v2, v[4:5], s[6:7] offset:88
.LBB0_599:
	s_or_b64 exec, exec, s[8:9]
	s_waitcnt lgkmcnt(0)
	ds_read_b32 v3, v69 offset:64
	v_mov_b32_e32 v0, 0x10000
	v_lshl_or_b32 v0, v68, 12, v0
	v_lshl_add_u64 v[4:5], v[66:67], 0, v[0:1]
	s_waitcnt lgkmcnt(0)
	v_mul_f32_e32 v0, v58, v3
	v_bfe_u32 v6, v0, 16, 1
	v_add3_u32 v6, v0, v6, s47
	global_store_short_d16_hi v[4:5], v6, off
	v_mul_f32_e32 v6, v42, v3
	v_mul_f32_e32 v7, v6, v6
	v_fmac_f32_e32 v7, v0, v0
	v_bfe_u32 v0, v6, 16, 1
	v_add3_u32 v0, v6, v0, s47
	global_store_short_d16_hi v[4:5], v0, off offset:64
	v_mul_f32_e32 v0, v26, v3
	v_bfe_u32 v6, v0, 16, 1
	v_fmac_f32_e32 v7, v0, v0
	v_add3_u32 v0, v0, v6, s47
	global_store_short_d16_hi v[4:5], v0, off offset:128
	v_mul_f32_e32 v0, v10, v3
	v_bfe_u32 v3, v0, 16, 1
	v_fmac_f32_e32 v7, v0, v0
	v_add3_u32 v0, v0, v3, s47
	global_store_short_d16_hi v[4:5], v0, off offset:192
	s_waitcnt lgkmcnt(0)
	s_nop 1
	v_add_f32_dpp v0, v7, v7 quad_perm:[1,0,3,2] row_mask:0xf bank_mask:0xf
	s_waitcnt lgkmcnt(0)
	s_nop 1
	v_add_f32_dpp v0, v0, v0 quad_perm:[2,3,0,1] row_mask:0xf bank_mask:0xf
	s_waitcnt lgkmcnt(0)
	s_nop 1
	v_add_f32_dpp v0, v0, v0 row_half_mirror row_mask:0xf bank_mask:0xf
	s_waitcnt lgkmcnt(0)
	s_nop 1
	v_add_f32_dpp v0, v0, v0 row_mirror row_mask:0xf bank_mask:0xf
	ds_bpermute_b32 v3, v249, v0
	s_and_saveexec_b64 s[8:9], vcc
	s_cbranch_execz .LBB0_601
	s_waitcnt lgkmcnt(0)
	v_add_f32_e32 v0, v0, v3
	v_fma_f32 v0, v0, s81, 0.5
	v_trunc_f32_e32 v0, v0
	v_mul_f32_e32 v3, 0x2f800000, v0
	v_floor_f32_e32 v3, v3
	v_fmac_f32_e32 v0, 0xcf800000, v3
	v_cvt_u32_f32_e32 v4, v0
	v_cvt_u32_f32_e32 v5, v3
	global_atomic_add_x2 v2, v[4:5], s[6:7] offset:128
.LBB0_601:
	s_or_b64 exec, exec, s[8:9]
	s_waitcnt lgkmcnt(0)
	ds_read_b32 v3, v69 offset:68
	v_mov_b32_e32 v0, 0x11000
	v_lshl_or_b32 v0, v68, 12, v0
	v_lshl_add_u64 v[4:5], v[66:67], 0, v[0:1]
	s_waitcnt lgkmcnt(0)
	v_mul_f32_e32 v0, v59, v3
	v_bfe_u32 v6, v0, 16, 1
	v_add3_u32 v6, v0, v6, s47
	global_store_short_d16_hi v[4:5], v6, off
	v_mul_f32_e32 v6, v43, v3
	v_mul_f32_e32 v7, v6, v6
	v_fmac_f32_e32 v7, v0, v0
	v_bfe_u32 v0, v6, 16, 1
	v_add3_u32 v0, v6, v0, s47
	global_store_short_d16_hi v[4:5], v0, off offset:64
	v_mul_f32_e32 v0, v27, v3
	v_bfe_u32 v6, v0, 16, 1
	v_fmac_f32_e32 v7, v0, v0
	v_add3_u32 v0, v0, v6, s47
	global_store_short_d16_hi v[4:5], v0, off offset:128
	v_mul_f32_e32 v0, v11, v3
	v_bfe_u32 v3, v0, 16, 1
	v_fmac_f32_e32 v7, v0, v0
	v_add3_u32 v0, v0, v3, s47
	global_store_short_d16_hi v[4:5], v0, off offset:192
	s_waitcnt lgkmcnt(0)
	s_nop 1
	v_add_f32_dpp v0, v7, v7 quad_perm:[1,0,3,2] row_mask:0xf bank_mask:0xf
	s_waitcnt lgkmcnt(0)
	s_nop 1
	v_add_f32_dpp v0, v0, v0 quad_perm:[2,3,0,1] row_mask:0xf bank_mask:0xf
	s_waitcnt lgkmcnt(0)
	s_nop 1
	v_add_f32_dpp v0, v0, v0 row_half_mirror row_mask:0xf bank_mask:0xf
	s_waitcnt lgkmcnt(0)
	s_nop 1
	v_add_f32_dpp v0, v0, v0 row_mirror row_mask:0xf bank_mask:0xf
	ds_bpermute_b32 v3, v249, v0
	s_and_saveexec_b64 s[8:9], vcc
	s_cbranch_execz .LBB0_603
	s_waitcnt lgkmcnt(0)
	v_add_f32_e32 v0, v0, v3
	v_fma_f32 v0, v0, s81, 0.5
	v_trunc_f32_e32 v0, v0
	v_mul_f32_e32 v3, 0x2f800000, v0
	v_floor_f32_e32 v3, v3
	v_fmac_f32_e32 v0, 0xcf800000, v3
	v_cvt_u32_f32_e32 v4, v0
	v_cvt_u32_f32_e32 v5, v3
	global_atomic_add_x2 v2, v[4:5], s[6:7] offset:136
.LBB0_603:
	s_or_b64 exec, exec, s[8:9]
	s_waitcnt lgkmcnt(0)
	ds_read_b32 v3, v69 offset:72
	v_mov_b32_e32 v0, 0x12000
	v_lshl_or_b32 v0, v68, 12, v0
	v_lshl_add_u64 v[4:5], v[66:67], 0, v[0:1]
	s_waitcnt lgkmcnt(0)
	v_mul_f32_e32 v0, v60, v3
	v_bfe_u32 v6, v0, 16, 1
	v_add3_u32 v6, v0, v6, s47
	global_store_short_d16_hi v[4:5], v6, off
	v_mul_f32_e32 v6, v44, v3
	v_mul_f32_e32 v7, v6, v6
	v_fmac_f32_e32 v7, v0, v0
	v_bfe_u32 v0, v6, 16, 1
	v_add3_u32 v0, v6, v0, s47
	global_store_short_d16_hi v[4:5], v0, off offset:64
	v_mul_f32_e32 v0, v28, v3
	v_bfe_u32 v6, v0, 16, 1
	v_fmac_f32_e32 v7, v0, v0
	v_add3_u32 v0, v0, v6, s47
	global_store_short_d16_hi v[4:5], v0, off offset:128
	v_mul_f32_e32 v0, v12, v3
	v_bfe_u32 v3, v0, 16, 1
	v_fmac_f32_e32 v7, v0, v0
	v_add3_u32 v0, v0, v3, s47
	global_store_short_d16_hi v[4:5], v0, off offset:192
	s_waitcnt lgkmcnt(0)
	s_nop 1
	v_add_f32_dpp v0, v7, v7 quad_perm:[1,0,3,2] row_mask:0xf bank_mask:0xf
	s_waitcnt lgkmcnt(0)
	s_nop 1
	v_add_f32_dpp v0, v0, v0 quad_perm:[2,3,0,1] row_mask:0xf bank_mask:0xf
	s_waitcnt lgkmcnt(0)
	s_nop 1
	v_add_f32_dpp v0, v0, v0 row_half_mirror row_mask:0xf bank_mask:0xf
	s_waitcnt lgkmcnt(0)
	s_nop 1
	v_add_f32_dpp v0, v0, v0 row_mirror row_mask:0xf bank_mask:0xf
	ds_bpermute_b32 v3, v249, v0
	s_and_saveexec_b64 s[8:9], vcc
	s_cbranch_execz .LBB0_605
	s_waitcnt lgkmcnt(0)
	v_add_f32_e32 v0, v0, v3
	v_fma_f32 v0, v0, s81, 0.5
	v_trunc_f32_e32 v0, v0
	v_mul_f32_e32 v3, 0x2f800000, v0
	v_floor_f32_e32 v3, v3
	v_fmac_f32_e32 v0, 0xcf800000, v3
	v_cvt_u32_f32_e32 v4, v0
	v_cvt_u32_f32_e32 v5, v3
	global_atomic_add_x2 v2, v[4:5], s[6:7] offset:144
.LBB0_605:
	s_or_b64 exec, exec, s[8:9]
	s_waitcnt lgkmcnt(0)
	ds_read_b32 v3, v69 offset:76
	v_mov_b32_e32 v0, 0x13000
	v_lshl_or_b32 v0, v68, 12, v0
	v_lshl_add_u64 v[4:5], v[66:67], 0, v[0:1]
	s_waitcnt lgkmcnt(0)
	v_mul_f32_e32 v0, v61, v3
	v_bfe_u32 v6, v0, 16, 1
	v_add3_u32 v6, v0, v6, s47
	global_store_short_d16_hi v[4:5], v6, off
	v_mul_f32_e32 v6, v45, v3
	v_mul_f32_e32 v7, v6, v6
	v_fmac_f32_e32 v7, v0, v0
	v_bfe_u32 v0, v6, 16, 1
	v_add3_u32 v0, v6, v0, s47
	global_store_short_d16_hi v[4:5], v0, off offset:64
	v_mul_f32_e32 v0, v29, v3
	v_bfe_u32 v6, v0, 16, 1
	v_fmac_f32_e32 v7, v0, v0
	v_add3_u32 v0, v0, v6, s47
	global_store_short_d16_hi v[4:5], v0, off offset:128
	v_mul_f32_e32 v0, v13, v3
	v_bfe_u32 v3, v0, 16, 1
	v_fmac_f32_e32 v7, v0, v0
	v_add3_u32 v0, v0, v3, s47
	global_store_short_d16_hi v[4:5], v0, off offset:192
	s_waitcnt lgkmcnt(0)
	s_nop 1
	v_add_f32_dpp v0, v7, v7 quad_perm:[1,0,3,2] row_mask:0xf bank_mask:0xf
	s_waitcnt lgkmcnt(0)
	s_nop 1
	v_add_f32_dpp v0, v0, v0 quad_perm:[2,3,0,1] row_mask:0xf bank_mask:0xf
	s_waitcnt lgkmcnt(0)
	s_nop 1
	v_add_f32_dpp v0, v0, v0 row_half_mirror row_mask:0xf bank_mask:0xf
	s_waitcnt lgkmcnt(0)
	s_nop 1
	v_add_f32_dpp v0, v0, v0 row_mirror row_mask:0xf bank_mask:0xf
	ds_bpermute_b32 v3, v249, v0
	s_and_saveexec_b64 s[8:9], vcc
	s_cbranch_execz .LBB0_607
	s_waitcnt lgkmcnt(0)
	v_add_f32_e32 v0, v0, v3
	v_fma_f32 v0, v0, s81, 0.5
	v_trunc_f32_e32 v0, v0
	v_mul_f32_e32 v3, 0x2f800000, v0
	v_floor_f32_e32 v3, v3
	v_fmac_f32_e32 v0, 0xcf800000, v3
	v_cvt_u32_f32_e32 v4, v0
	v_cvt_u32_f32_e32 v5, v3
	global_atomic_add_x2 v2, v[4:5], s[6:7] offset:152
.LBB0_607:
	s_or_b64 exec, exec, s[8:9]
	s_waitcnt lgkmcnt(0)
	ds_read_b32 v3, v69 offset:96
	v_mov_b32_e32 v0, 0x18000
	v_lshl_or_b32 v0, v68, 12, v0
	v_lshl_add_u64 v[4:5], v[66:67], 0, v[0:1]
	s_waitcnt lgkmcnt(0)
	v_mul_f32_e32 v0, v62, v3
	v_bfe_u32 v6, v0, 16, 1
	v_add3_u32 v6, v0, v6, s47
	global_store_short_d16_hi v[4:5], v6, off
	v_mul_f32_e32 v6, v46, v3
	v_mul_f32_e32 v7, v6, v6
	v_fmac_f32_e32 v7, v0, v0
	v_bfe_u32 v0, v6, 16, 1
	v_add3_u32 v0, v6, v0, s47
	global_store_short_d16_hi v[4:5], v0, off offset:64
	v_mul_f32_e32 v0, v30, v3
	v_bfe_u32 v6, v0, 16, 1
	v_fmac_f32_e32 v7, v0, v0
	v_add3_u32 v0, v0, v6, s47
	global_store_short_d16_hi v[4:5], v0, off offset:128
	v_mul_f32_e32 v0, v14, v3
	v_bfe_u32 v3, v0, 16, 1
	v_fmac_f32_e32 v7, v0, v0
	v_add3_u32 v0, v0, v3, s47
	global_store_short_d16_hi v[4:5], v0, off offset:192
	s_waitcnt lgkmcnt(0)
	s_nop 1
	v_add_f32_dpp v0, v7, v7 quad_perm:[1,0,3,2] row_mask:0xf bank_mask:0xf
	s_waitcnt lgkmcnt(0)
	s_nop 1
	v_add_f32_dpp v0, v0, v0 quad_perm:[2,3,0,1] row_mask:0xf bank_mask:0xf
	s_waitcnt lgkmcnt(0)
	s_nop 1
	v_add_f32_dpp v0, v0, v0 row_half_mirror row_mask:0xf bank_mask:0xf
	s_waitcnt lgkmcnt(0)
	s_nop 1
	v_add_f32_dpp v0, v0, v0 row_mirror row_mask:0xf bank_mask:0xf
	ds_bpermute_b32 v3, v249, v0
	s_and_saveexec_b64 s[8:9], vcc
	s_cbranch_execz .LBB0_609
	s_waitcnt lgkmcnt(0)
	v_add_f32_e32 v0, v0, v3
	v_fma_f32 v0, v0, s81, 0.5
	v_trunc_f32_e32 v0, v0
	v_mul_f32_e32 v3, 0x2f800000, v0
	v_floor_f32_e32 v3, v3
	v_fmac_f32_e32 v0, 0xcf800000, v3
	v_cvt_u32_f32_e32 v4, v0
	v_cvt_u32_f32_e32 v5, v3
	global_atomic_add_x2 v2, v[4:5], s[6:7] offset:192
.LBB0_609:
	s_or_b64 exec, exec, s[8:9]
	s_waitcnt lgkmcnt(0)
	ds_read_b32 v3, v69 offset:100
	v_mov_b32_e32 v0, 0x19000
	v_lshl_or_b32 v0, v68, 12, v0
	v_lshl_add_u64 v[4:5], v[66:67], 0, v[0:1]
	s_waitcnt lgkmcnt(0)
	v_mul_f32_e32 v0, v63, v3
	v_bfe_u32 v6, v0, 16, 1
	v_add3_u32 v6, v0, v6, s47
	global_store_short_d16_hi v[4:5], v6, off
	v_mul_f32_e32 v6, v47, v3
	v_mul_f32_e32 v7, v6, v6
	v_fmac_f32_e32 v7, v0, v0
	v_bfe_u32 v0, v6, 16, 1
	v_add3_u32 v0, v6, v0, s47
	global_store_short_d16_hi v[4:5], v0, off offset:64
	v_mul_f32_e32 v0, v31, v3
	v_bfe_u32 v6, v0, 16, 1
	v_fmac_f32_e32 v7, v0, v0
	v_add3_u32 v0, v0, v6, s47
	global_store_short_d16_hi v[4:5], v0, off offset:128
	v_mul_f32_e32 v0, v15, v3
	v_bfe_u32 v3, v0, 16, 1
	v_fmac_f32_e32 v7, v0, v0
	v_add3_u32 v0, v0, v3, s47
	global_store_short_d16_hi v[4:5], v0, off offset:192
	s_waitcnt lgkmcnt(0)
	s_nop 1
	v_add_f32_dpp v0, v7, v7 quad_perm:[1,0,3,2] row_mask:0xf bank_mask:0xf
	s_waitcnt lgkmcnt(0)
	s_nop 1
	v_add_f32_dpp v0, v0, v0 quad_perm:[2,3,0,1] row_mask:0xf bank_mask:0xf
	s_waitcnt lgkmcnt(0)
	s_nop 1
	v_add_f32_dpp v0, v0, v0 row_half_mirror row_mask:0xf bank_mask:0xf
	s_waitcnt lgkmcnt(0)
	s_nop 1
	v_add_f32_dpp v0, v0, v0 row_mirror row_mask:0xf bank_mask:0xf
	ds_bpermute_b32 v3, v249, v0
	s_and_saveexec_b64 s[8:9], vcc
	s_cbranch_execz .LBB0_611
	s_waitcnt lgkmcnt(0)
	v_add_f32_e32 v0, v0, v3
	v_fma_f32 v0, v0, s81, 0.5
	v_trunc_f32_e32 v0, v0
	v_mul_f32_e32 v3, 0x2f800000, v0
	v_floor_f32_e32 v3, v3
	v_fmac_f32_e32 v0, 0xcf800000, v3
	v_cvt_u32_f32_e32 v4, v0
	v_cvt_u32_f32_e32 v5, v3
	global_atomic_add_x2 v2, v[4:5], s[6:7] offset:200
.LBB0_611:
	s_or_b64 exec, exec, s[8:9]
	s_waitcnt lgkmcnt(0)
	ds_read_b32 v3, v69 offset:104
	v_mov_b32_e32 v0, 0x1a000
	v_lshl_or_b32 v0, v68, 12, v0
	v_lshl_add_u64 v[4:5], v[66:67], 0, v[0:1]
	s_waitcnt lgkmcnt(0)
	v_mul_f32_e32 v0, v64, v3
	v_bfe_u32 v6, v0, 16, 1
	v_add3_u32 v6, v0, v6, s47
	global_store_short_d16_hi v[4:5], v6, off
	v_mul_f32_e32 v6, v48, v3
	v_mul_f32_e32 v7, v6, v6
	v_fmac_f32_e32 v7, v0, v0
	v_bfe_u32 v0, v6, 16, 1
	v_add3_u32 v0, v6, v0, s47
	global_store_short_d16_hi v[4:5], v0, off offset:64
	v_mul_f32_e32 v0, v32, v3
	v_bfe_u32 v6, v0, 16, 1
	v_fmac_f32_e32 v7, v0, v0
	v_add3_u32 v0, v0, v6, s47
	global_store_short_d16_hi v[4:5], v0, off offset:128
	v_mul_f32_e32 v0, v16, v3
	v_bfe_u32 v3, v0, 16, 1
	v_fmac_f32_e32 v7, v0, v0
	v_add3_u32 v0, v0, v3, s47
	global_store_short_d16_hi v[4:5], v0, off offset:192
	s_waitcnt lgkmcnt(0)
	s_nop 1
	v_add_f32_dpp v0, v7, v7 quad_perm:[1,0,3,2] row_mask:0xf bank_mask:0xf
	s_waitcnt lgkmcnt(0)
	s_nop 1
	v_add_f32_dpp v0, v0, v0 quad_perm:[2,3,0,1] row_mask:0xf bank_mask:0xf
	s_waitcnt lgkmcnt(0)
	s_nop 1
	v_add_f32_dpp v0, v0, v0 row_half_mirror row_mask:0xf bank_mask:0xf
	s_waitcnt lgkmcnt(0)
	s_nop 1
	v_add_f32_dpp v0, v0, v0 row_mirror row_mask:0xf bank_mask:0xf
	ds_bpermute_b32 v3, v249, v0
	s_and_saveexec_b64 s[8:9], vcc
	s_cbranch_execz .LBB0_613
	s_waitcnt lgkmcnt(0)
	v_add_f32_e32 v0, v0, v3
	v_fma_f32 v0, v0, s81, 0.5
	v_trunc_f32_e32 v0, v0
	v_mul_f32_e32 v3, 0x2f800000, v0
	v_floor_f32_e32 v3, v3
	v_fmac_f32_e32 v0, 0xcf800000, v3
	v_cvt_u32_f32_e32 v4, v0
	v_cvt_u32_f32_e32 v5, v3
	global_atomic_add_x2 v2, v[4:5], s[6:7] offset:208
.LBB0_613:
	s_or_b64 exec, exec, s[8:9]
	ds_read_b32 v0, v69 offset:108
	s_waitcnt lgkmcnt(0)
	v_mul_f32_e32 v6, v49, v0
	v_mul_f32_e32 v3, v65, v0
	v_mul_f32_e32 v4, v6, v6
	v_mul_f32_e32 v7, v33, v0
	v_fmac_f32_e32 v4, v3, v3
	v_fmac_f32_e32 v4, v7, v7
	v_mul_f32_e32 v8, v17, v0
	v_fmac_f32_e32 v4, v8, v8
	s_waitcnt lgkmcnt(0)
	s_nop 1
	v_add_f32_dpp v9, v4, v4 quad_perm:[1,0,3,2] row_mask:0xf bank_mask:0xf
	v_mov_b32_e32 v0, 0x1b000
	v_lshl_or_b32 v0, v68, 12, v0
	v_lshl_add_u64 v[4:5], v[66:67], 0, v[0:1]
	s_waitcnt lgkmcnt(0)
	s_nop 1
	v_add_f32_dpp v0, v9, v9 quad_perm:[2,3,0,1] row_mask:0xf bank_mask:0xf
	v_bfe_u32 v10, v3, 16, 1
	v_add3_u32 v3, v3, v10, s47
	global_store_short_d16_hi v[4:5], v3, off
	v_bfe_u32 v3, v6, 16, 1
	s_waitcnt lgkmcnt(0)
	s_nop 1
	v_add_f32_dpp v0, v0, v0 row_half_mirror row_mask:0xf bank_mask:0xf
	v_add3_u32 v3, v6, v3, s47
	global_store_short_d16_hi v[4:5], v3, off offset:64
	v_bfe_u32 v3, v7, 16, 1
	v_add3_u32 v6, v7, v3, s47
	s_waitcnt lgkmcnt(0)
	s_nop 1
	v_add_f32_dpp v0, v0, v0 row_mirror row_mask:0xf bank_mask:0xf
	ds_bpermute_b32 v3, v249, v0
	global_store_short_d16_hi v[4:5], v6, off offset:128
	v_bfe_u32 v6, v8, 16, 1
	v_add3_u32 v6, v8, v6, s47
	global_store_short_d16_hi v[4:5], v6, off offset:192
	s_and_saveexec_b64 s[8:9], vcc
	s_cbranch_execz .LBB0_528
	s_waitcnt lgkmcnt(0)
	v_add_f32_e32 v0, v0, v3
	v_fma_f32 v0, v0, s81, 0.5
	v_trunc_f32_e32 v0, v0
	v_mul_f32_e32 v3, 0x2f800000, v0
	v_floor_f32_e32 v3, v3
	v_fmac_f32_e32 v0, 0xcf800000, v3
	v_cvt_u32_f32_e32 v4, v0
	v_cvt_u32_f32_e32 v5, v3
	global_atomic_add_x2 v2, v[4:5], s[6:7] offset:216
	s_branch .LBB0_528
